# EpiResid epilogues (w_o and down GEMM residual): flat ops to global, four full vmcnt(0) drains replaced by counted vmcnt at first use of each loaded batch
# baseline (speedup 1.0000x reference)
.LBB0_92:
	s_add_u32 s20, s18, 0xfffc0080
	s_addc_u32 s21, s19, -1
	s_add_i32 s61, 0, 0x10000
	v_add_u32_e32 v78, s61, v161
	ds_read_b128 v[66:69], v78
	ds_read_b128 v[70:73], v78 offset:1024
	ds_read_b128 v[74:77], v78 offset:2048
	ds_read_b128 v[78:81], v78 offset:3072
	s_cmp_eq_u32 s60, 12
	s_cselect_b32 s23, s11, s21
	s_cselect_b32 s22, s36, s20
	s_cselect_b32 s21, s13, s39
	s_cselect_b32 s20, s37, s38
	v_lshl_add_u64 v[164:165], s[18:19], 0, v[150:151]
	s_add_i32 m0, s25, 0xc000
	ds_read_b128 v[152:155], v163
	ds_read_b128 v[156:159], v163 offset:1024
	ds_read_b128 v[182:185], v163 offset:2048
	ds_read_b128 v[186:189], v163 offset:3072
	ds_read_b128 v[190:193], v163 offset:4096
	ds_read_b128 v[194:197], v163 offset:5120
	ds_read_b128 v[198:201], v163 offset:6144
	ds_read_b128 v[202:205], v163 offset:7168
	global_load_lds_dwordx4 v[164:165], off
	v_lshl_add_u64 v[164:165], s[18:19], 0, v[148:149]
	s_add_i32 m0, s25, 0xe000
	s_nop 0
	global_load_lds_dwordx4 v[164:165], off
	s_waitcnt lgkmcnt(8)
	s_barrier
	s_waitcnt lgkmcnt(0)
	s_setprio 1
	s_waitcnt lgkmcnt(0)
	v_mfma_f32_16x16x32_bf16 v[142:145], v[66:69], v[152:155], v[142:145]
	v_mfma_f32_16x16x32_bf16 v[138:141], v[74:77], v[152:155], v[138:141]
	v_mfma_f32_16x16x32_bf16 v[126:129], v[66:69], v[182:185], v[126:129]
	v_mfma_f32_16x16x32_bf16 v[122:125], v[74:77], v[182:185], v[122:125]
	v_mfma_f32_16x16x32_bf16 v[110:113], v[66:69], v[190:193], v[110:113]
	v_mfma_f32_16x16x32_bf16 v[106:109], v[74:77], v[190:193], v[106:109]
	v_mfma_f32_16x16x32_bf16 v[102:105], v[66:69], v[198:201], v[102:105]
	v_mfma_f32_16x16x32_bf16 v[98:101], v[74:77], v[198:201], v[98:101]
	v_mfma_f32_16x16x32_bf16 v[142:145], v[70:73], v[156:159], v[142:145]
	v_mfma_f32_16x16x32_bf16 v[138:141], v[78:81], v[156:159], v[138:141]
	v_mfma_f32_16x16x32_bf16 v[126:129], v[70:73], v[186:189], v[126:129]
	v_mfma_f32_16x16x32_bf16 v[122:125], v[78:81], v[186:189], v[122:125]
	v_mfma_f32_16x16x32_bf16 v[110:113], v[70:73], v[194:197], v[110:113]
	v_mfma_f32_16x16x32_bf16 v[106:109], v[78:81], v[194:197], v[106:109]
	v_mfma_f32_16x16x32_bf16 v[102:105], v[70:73], v[202:205], v[102:105]
	v_mfma_f32_16x16x32_bf16 v[98:101], v[78:81], v[202:205], v[98:101]
	s_setprio 0
	s_barrier
	s_add_i32 s65, 0, 0x14000
	v_add_u32_e32 v164, s65, v161
	s_add_i32 s61, s61, s24
	ds_read_b128 v[206:209], v164
	ds_read_b128 v[210:213], v164 offset:1024
	ds_read_b128 v[230:233], v164 offset:2048
	ds_read_b128 v[234:237], v164 offset:3072
	v_lshl_add_u64 v[164:165], s[20:21], 0, v[0:1]
	s_mov_b32 m0, s61
	v_lshl_add_u64 v[228:229], s[20:21], 0, v[146:147]
	global_load_lds_dwordx4 v[164:165], off
	s_add_i32 m0, s61, 0x2000
	s_nop 0
	global_load_lds_dwordx4 v[228:229], off
	s_barrier
	s_waitcnt lgkmcnt(0)
	s_setprio 1
	s_waitcnt lgkmcnt(0)
	v_mfma_f32_16x16x32_bf16 v[134:137], v[206:209], v[152:155], v[134:137]
	v_mfma_f32_16x16x32_bf16 v[130:133], v[230:233], v[152:155], v[130:133]
	v_mfma_f32_16x16x32_bf16 v[118:121], v[206:209], v[182:185], v[118:121]
	v_mfma_f32_16x16x32_bf16 v[114:117], v[230:233], v[182:185], v[114:117]
	v_mfma_f32_16x16x32_bf16 v[94:97], v[206:209], v[190:193], v[94:97]
	v_mfma_f32_16x16x32_bf16 v[90:93], v[230:233], v[190:193], v[90:93]
	v_mfma_f32_16x16x32_bf16 v[86:89], v[206:209], v[198:201], v[86:89]
	v_mfma_f32_16x16x32_bf16 v[82:85], v[230:233], v[198:201], v[82:85]
	v_mfma_f32_16x16x32_bf16 v[134:137], v[210:213], v[156:159], v[134:137]
	v_mfma_f32_16x16x32_bf16 v[130:133], v[234:237], v[156:159], v[130:133]
	v_mfma_f32_16x16x32_bf16 v[118:121], v[210:213], v[186:189], v[118:121]
	v_mfma_f32_16x16x32_bf16 v[114:117], v[234:237], v[186:189], v[114:117]
	v_mfma_f32_16x16x32_bf16 v[94:97], v[210:213], v[194:197], v[94:97]
	v_mfma_f32_16x16x32_bf16 v[90:93], v[234:237], v[194:197], v[90:93]
	v_mfma_f32_16x16x32_bf16 v[86:89], v[210:213], v[202:205], v[86:89]
	v_mfma_f32_16x16x32_bf16 v[82:85], v[234:237], v[202:205], v[82:85]
	s_setprio 0
	s_mov_b32 m0, s25
	v_lshl_add_u64 v[238:239], s[22:23], 0, v[0:1]
	s_barrier
	ds_read_b128 v[152:155], v163 offset:16384
	ds_read_b128 v[156:159], v163 offset:17408
	ds_read_b128 v[182:185], v163 offset:18432
	ds_read_b128 v[186:189], v163 offset:19456
	ds_read_b128 v[190:193], v163 offset:20480
	ds_read_b128 v[194:197], v163 offset:21504
	ds_read_b128 v[198:201], v163 offset:22528
	ds_read_b128 v[202:205], v163 offset:23552
	global_load_lds_dwordx4 v[238:239], off
	v_lshl_add_u64 v[240:241], s[22:23], 0, v[146:147]
	s_mov_b32 m0, s26
	s_nop 0
	global_load_lds_dwordx4 v[240:241], off
	s_barrier
	s_waitcnt lgkmcnt(0)
	s_setprio 1
	s_waitcnt lgkmcnt(0)
	v_mfma_f32_16x16x32_bf16 v[62:65], v[66:69], v[152:155], v[62:65]
	v_mfma_f32_16x16x32_bf16 v[58:61], v[74:77], v[152:155], v[58:61]
	v_mfma_f32_16x16x32_bf16 v[46:49], v[66:69], v[182:185], v[46:49]
	v_mfma_f32_16x16x32_bf16 v[42:45], v[74:77], v[182:185], v[42:45]
	v_mfma_f32_16x16x32_bf16 v[30:33], v[66:69], v[190:193], v[30:33]
	v_mfma_f32_16x16x32_bf16 v[26:29], v[74:77], v[190:193], v[26:29]
	v_mfma_f32_16x16x32_bf16 v[22:25], v[66:69], v[198:201], v[22:25]
	v_mfma_f32_16x16x32_bf16 v[18:21], v[74:77], v[198:201], v[18:21]
	v_mfma_f32_16x16x32_bf16 v[62:65], v[70:73], v[156:159], v[62:65]
	v_mfma_f32_16x16x32_bf16 v[58:61], v[78:81], v[156:159], v[58:61]
	v_mfma_f32_16x16x32_bf16 v[46:49], v[70:73], v[186:189], v[46:49]
	v_mfma_f32_16x16x32_bf16 v[42:45], v[78:81], v[186:189], v[42:45]
	v_mfma_f32_16x16x32_bf16 v[30:33], v[70:73], v[194:197], v[30:33]
	v_mfma_f32_16x16x32_bf16 v[26:29], v[78:81], v[194:197], v[26:29]
	v_mfma_f32_16x16x32_bf16 v[22:25], v[70:73], v[202:205], v[22:25]
	v_mfma_f32_16x16x32_bf16 v[18:21], v[78:81], v[202:205], v[18:21]
	s_setprio 0
	s_barrier
	s_add_u32 s62, s20, 0x40000
	s_addc_u32 s63, s21, 0
	s_add_i32 s61, s65, s24
	v_lshl_add_u64 v[66:67], s[62:63], 0, v[0:1]
	s_mov_b32 m0, s61
	s_nop 0
	global_load_lds_dwordx4 v[66:67], off
	v_lshl_add_u64 v[66:67], s[62:63], 0, v[146:147]
	s_add_i32 m0, s61, 0x2000
	s_nop 0
	global_load_lds_dwordx4 v[66:67], off
	s_waitcnt vmcnt(6)
	s_barrier
	s_setprio 1
	v_mfma_f32_16x16x32_bf16 v[54:57], v[206:209], v[152:155], v[54:57]
	v_mfma_f32_16x16x32_bf16 v[50:53], v[230:233], v[152:155], v[50:53]
	v_mfma_f32_16x16x32_bf16 v[38:41], v[206:209], v[182:185], v[38:41]
	v_mfma_f32_16x16x32_bf16 v[34:37], v[230:233], v[182:185], v[34:37]
	v_mfma_f32_16x16x32_bf16 v[14:17], v[206:209], v[190:193], v[14:17]
	v_mfma_f32_16x16x32_bf16 v[10:13], v[230:233], v[190:193], v[10:13]
	v_mfma_f32_16x16x32_bf16 v[6:9], v[206:209], v[198:201], v[6:9]
	v_mfma_f32_16x16x32_bf16 v[2:5], v[230:233], v[198:201], v[2:5]
	v_mfma_f32_16x16x32_bf16 v[54:57], v[210:213], v[156:159], v[54:57]
	v_mfma_f32_16x16x32_bf16 v[50:53], v[234:237], v[156:159], v[50:53]
	v_mfma_f32_16x16x32_bf16 v[38:41], v[210:213], v[186:189], v[38:41]
	v_mfma_f32_16x16x32_bf16 v[34:37], v[234:237], v[186:189], v[34:37]
	v_mfma_f32_16x16x32_bf16 v[14:17], v[210:213], v[194:197], v[14:17]
	v_mfma_f32_16x16x32_bf16 v[10:13], v[234:237], v[194:197], v[10:13]
	v_mfma_f32_16x16x32_bf16 v[6:9], v[210:213], v[202:205], v[6:9]
	v_mfma_f32_16x16x32_bf16 v[2:5], v[234:237], v[202:205], v[2:5]
	s_setprio 0
	s_add_i32 s61, 0, 0x18000
	v_add_u32_e32 v78, s61, v161
	s_barrier
	ds_read_b128 v[66:69], v78
	ds_read_b128 v[70:73], v78 offset:1024
	ds_read_b128 v[74:77], v78 offset:2048
	ds_read_b128 v[78:81], v78 offset:3072
	s_add_u32 s22, s22, 0x40000
	s_addc_u32 s23, s23, 0
	s_mov_b32 m0, s27
	v_lshl_add_u64 v[206:207], s[22:23], 0, v[0:1]
	ds_read_b128 v[152:155], v163 offset:32768
	ds_read_b128 v[156:159], v163 offset:33792
	ds_read_b128 v[182:185], v163 offset:34816
	ds_read_b128 v[186:189], v163 offset:35840
	ds_read_b128 v[190:193], v163 offset:36864
	ds_read_b128 v[194:197], v163 offset:37888
	ds_read_b128 v[198:201], v163 offset:38912
	ds_read_b128 v[202:205], v163 offset:39936
	global_load_lds_dwordx4 v[206:207], off
	v_lshl_add_u64 v[206:207], s[22:23], 0, v[146:147]
	s_mov_b32 m0, s28
	s_nop 0
	global_load_lds_dwordx4 v[206:207], off
	s_waitcnt lgkmcnt(8)
	s_barrier
	s_waitcnt lgkmcnt(0)
	s_setprio 1
	s_waitcnt lgkmcnt(0)
	v_mfma_f32_16x16x32_bf16 v[142:145], v[66:69], v[152:155], v[142:145]
	v_mfma_f32_16x16x32_bf16 v[138:141], v[74:77], v[152:155], v[138:141]
	v_mfma_f32_16x16x32_bf16 v[126:129], v[66:69], v[182:185], v[126:129]
	v_mfma_f32_16x16x32_bf16 v[122:125], v[74:77], v[182:185], v[122:125]
	v_mfma_f32_16x16x32_bf16 v[110:113], v[66:69], v[190:193], v[110:113]
	v_mfma_f32_16x16x32_bf16 v[106:109], v[74:77], v[190:193], v[106:109]
	v_mfma_f32_16x16x32_bf16 v[102:105], v[66:69], v[198:201], v[102:105]
	v_mfma_f32_16x16x32_bf16 v[98:101], v[74:77], v[198:201], v[98:101]
	v_mfma_f32_16x16x32_bf16 v[142:145], v[70:73], v[156:159], v[142:145]
	v_mfma_f32_16x16x32_bf16 v[138:141], v[78:81], v[156:159], v[138:141]
	v_mfma_f32_16x16x32_bf16 v[126:129], v[70:73], v[186:189], v[126:129]
	v_mfma_f32_16x16x32_bf16 v[122:125], v[78:81], v[186:189], v[122:125]
	v_mfma_f32_16x16x32_bf16 v[110:113], v[70:73], v[194:197], v[110:113]
	v_mfma_f32_16x16x32_bf16 v[106:109], v[78:81], v[194:197], v[106:109]
	v_mfma_f32_16x16x32_bf16 v[102:105], v[70:73], v[202:205], v[102:105]
	v_mfma_f32_16x16x32_bf16 v[98:101], v[78:81], v[202:205], v[98:101]
	s_setprio 0
	s_barrier
	s_add_i32 s22, 0, 0x1c000
	s_add_i32 s23, s61, s24
	v_add_u32_e32 v169, s22, v161
	v_lshl_add_u64 v[164:165], v[164:165], 0, s[94:95]
	s_mov_b32 m0, s23
	ds_read_b128 v[206:209], v169
	ds_read_b128 v[210:213], v169 offset:1024
	ds_read_b128 v[230:233], v169 offset:2048
	ds_read_b128 v[234:237], v169 offset:3072
	global_load_lds_dwordx4 v[164:165], off
	v_lshl_add_u64 v[164:165], v[228:229], 0, s[94:95]
	s_add_i32 m0, s23, 0x2000
	s_nop 0
	global_load_lds_dwordx4 v[164:165], off
	s_barrier
	s_waitcnt lgkmcnt(0)
	s_setprio 1
	s_waitcnt lgkmcnt(0)
	v_mfma_f32_16x16x32_bf16 v[134:137], v[206:209], v[152:155], v[134:137]
	v_mfma_f32_16x16x32_bf16 v[130:133], v[230:233], v[152:155], v[130:133]
	v_mfma_f32_16x16x32_bf16 v[118:121], v[206:209], v[182:185], v[118:121]
	v_mfma_f32_16x16x32_bf16 v[114:117], v[230:233], v[182:185], v[114:117]
	v_mfma_f32_16x16x32_bf16 v[94:97], v[206:209], v[190:193], v[94:97]
	v_mfma_f32_16x16x32_bf16 v[90:93], v[230:233], v[190:193], v[90:93]
	v_mfma_f32_16x16x32_bf16 v[86:89], v[206:209], v[198:201], v[86:89]
	v_mfma_f32_16x16x32_bf16 v[82:85], v[230:233], v[198:201], v[82:85]
	v_mfma_f32_16x16x32_bf16 v[134:137], v[210:213], v[156:159], v[134:137]
	v_mfma_f32_16x16x32_bf16 v[130:133], v[234:237], v[156:159], v[130:133]
	v_mfma_f32_16x16x32_bf16 v[118:121], v[210:213], v[186:189], v[118:121]
	v_mfma_f32_16x16x32_bf16 v[114:117], v[234:237], v[186:189], v[114:117]
	v_mfma_f32_16x16x32_bf16 v[94:97], v[210:213], v[194:197], v[94:97]
	v_mfma_f32_16x16x32_bf16 v[90:93], v[234:237], v[194:197], v[90:93]
	v_mfma_f32_16x16x32_bf16 v[86:89], v[210:213], v[202:205], v[86:89]
	v_mfma_f32_16x16x32_bf16 v[82:85], v[234:237], v[202:205], v[82:85]
	s_setprio 0
	s_mov_b32 m0, s29
	v_lshl_add_u64 v[164:165], v[238:239], 0, s[94:95]
	s_barrier
	ds_read_b128 v[152:155], v163 offset:49152
	ds_read_b128 v[156:159], v163 offset:50176
	ds_read_b128 v[182:185], v163 offset:51200
	ds_read_b128 v[186:189], v163 offset:52224
	ds_read_b128 v[190:193], v163 offset:53248
	ds_read_b128 v[194:197], v163 offset:54272
	ds_read_b128 v[198:201], v163 offset:55296
	ds_read_b128 v[202:205], v163 offset:56320
	global_load_lds_dwordx4 v[164:165], off
	v_lshl_add_u64 v[164:165], v[240:241], 0, s[94:95]
	s_mov_b32 m0, s30
	s_nop 0
	global_load_lds_dwordx4 v[164:165], off
	s_barrier
	s_waitcnt lgkmcnt(0)
	s_setprio 1
	s_waitcnt lgkmcnt(0)
	v_mfma_f32_16x16x32_bf16 v[62:65], v[66:69], v[152:155], v[62:65]
	v_mfma_f32_16x16x32_bf16 v[58:61], v[74:77], v[152:155], v[58:61]
	v_mfma_f32_16x16x32_bf16 v[46:49], v[66:69], v[182:185], v[46:49]
	v_mfma_f32_16x16x32_bf16 v[42:45], v[74:77], v[182:185], v[42:45]
	v_mfma_f32_16x16x32_bf16 v[30:33], v[66:69], v[190:193], v[30:33]
	v_mfma_f32_16x16x32_bf16 v[26:29], v[74:77], v[190:193], v[26:29]
	v_mfma_f32_16x16x32_bf16 v[22:25], v[66:69], v[198:201], v[22:25]
	v_mfma_f32_16x16x32_bf16 v[18:21], v[74:77], v[198:201], v[18:21]
	v_mfma_f32_16x16x32_bf16 v[62:65], v[70:73], v[156:159], v[62:65]
	v_mfma_f32_16x16x32_bf16 v[58:61], v[78:81], v[156:159], v[58:61]
	v_mfma_f32_16x16x32_bf16 v[46:49], v[70:73], v[186:189], v[46:49]
	v_mfma_f32_16x16x32_bf16 v[42:45], v[78:81], v[186:189], v[42:45]
	v_mfma_f32_16x16x32_bf16 v[30:33], v[70:73], v[194:197], v[30:33]
	v_mfma_f32_16x16x32_bf16 v[26:29], v[78:81], v[194:197], v[26:29]
	v_mfma_f32_16x16x32_bf16 v[22:25], v[70:73], v[202:205], v[22:25]
	v_mfma_f32_16x16x32_bf16 v[18:21], v[78:81], v[202:205], v[18:21]
	s_setprio 0
	s_barrier
	s_add_u32 s20, s20, 0x40080
	s_addc_u32 s21, s21, 0
	s_add_i32 s22, s22, s24
	v_lshl_add_u64 v[66:67], s[20:21], 0, v[0:1]
	s_mov_b32 m0, s22
	s_nop 0
	global_load_lds_dwordx4 v[66:67], off
	v_lshl_add_u64 v[66:67], s[20:21], 0, v[146:147]
	s_add_i32 m0, s22, 0x2000
	s_nop 0
	global_load_lds_dwordx4 v[66:67], off
	s_waitcnt vmcnt(6)
	s_barrier
	s_setprio 1
	v_mfma_f32_16x16x32_bf16 v[54:57], v[206:209], v[152:155], v[54:57]
	v_mfma_f32_16x16x32_bf16 v[50:53], v[230:233], v[152:155], v[50:53]
	v_mfma_f32_16x16x32_bf16 v[38:41], v[206:209], v[182:185], v[38:41]
	v_mfma_f32_16x16x32_bf16 v[34:37], v[230:233], v[182:185], v[34:37]
	v_mfma_f32_16x16x32_bf16 v[14:17], v[206:209], v[190:193], v[14:17]
	v_mfma_f32_16x16x32_bf16 v[10:13], v[230:233], v[190:193], v[10:13]
	v_mfma_f32_16x16x32_bf16 v[6:9], v[206:209], v[198:201], v[6:9]
	v_mfma_f32_16x16x32_bf16 v[2:5], v[230:233], v[198:201], v[2:5]
	v_mfma_f32_16x16x32_bf16 v[54:57], v[210:213], v[156:159], v[54:57]
	v_mfma_f32_16x16x32_bf16 v[50:53], v[234:237], v[156:159], v[50:53]
	v_mfma_f32_16x16x32_bf16 v[38:41], v[210:213], v[186:189], v[38:41]
	v_mfma_f32_16x16x32_bf16 v[34:37], v[234:237], v[186:189], v[34:37]
	v_mfma_f32_16x16x32_bf16 v[14:17], v[210:213], v[194:197], v[14:17]
	v_mfma_f32_16x16x32_bf16 v[10:13], v[234:237], v[194:197], v[10:13]
	v_mfma_f32_16x16x32_bf16 v[6:9], v[210:213], v[202:205], v[6:9]
	v_mfma_f32_16x16x32_bf16 v[2:5], v[234:237], v[202:205], v[2:5]
	s_setprio 0
	s_add_i32 s60, s60, 2
	s_add_u32 s38, s38, 0x100
	s_addc_u32 s39, s39, 0
	s_add_u32 s18, s18, 0x100
	s_addc_u32 s19, s19, 0
	s_cmp_gt_u32 s60, 13
	s_barrier
	s_cbranch_scc0 .LBB0_92
	s_ashr_i32 s11, s34, 4
	v_lshl_add_u32 v154, s34, 8, v160
	s_mul_hi_i32 s13, s11, 0x6000
	s_mulk_i32 s11, 0x6000
	v_lshl_or_b32 v66, s35, 8, v162
	v_ashrrev_i32_e32 v155, 31, v154
	s_add_u32 s18, s0, s11
	v_ashrrev_i32_e32 v67, 31, v66
	v_lshlrev_b64 v[156:157], 12, v[154:155]
	s_addc_u32 s19, s1, s13
	v_lshlrev_b64 v[152:153], 2, v[66:67]
	v_lshl_add_u64 v[158:159], s[78:79], 0, v[156:157]
	v_lshl_add_u64 v[66:67], s[18:19], 0, v[152:153]
	v_lshl_add_u64 v[158:159], v[158:159], 0, v[152:153]
	global_load_dwordx4 v[78:81], v[66:67], off
	global_load_dwordx4 v[74:77], v[66:67], off offset:64
	global_load_dwordx4 v[70:73], v[66:67], off offset:512
	s_nop 0
	global_load_dwordx4 v[66:69], v[66:67], off offset:576
	s_nop 0
	global_load_dwordx4 v[182:185], v[158:159], off
	global_load_dwordx4 v[186:189], v[158:159], off offset:64
	global_load_dwordx4 v[190:193], v[158:159], off offset:512
	global_load_dwordx4 v[194:197], v[158:159], off offset:576
	v_or_b32_e32 v158, 16, v154
	v_ashrrev_i32_e32 v159, 31, v158
	v_lshlrev_b64 v[164:165], 12, v[158:159]
	v_lshl_add_u64 v[158:159], s[78:79], 0, v[164:165]
	v_lshl_add_u64 v[158:159], v[158:159], 0, v[152:153]
	global_load_dwordx4 v[198:201], v[158:159], off
	global_load_dwordx4 v[202:205], v[158:159], off offset:64
	global_load_dwordx4 v[206:209], v[158:159], off offset:512
	global_load_dwordx4 v[210:213], v[158:159], off offset:576
	v_lshl_add_u64 v[158:159], s[76:77], 0, v[156:157]
	v_lshl_add_u64 v[158:159], v[158:159], 0, v[152:153]
	v_lshl_add_u64 v[164:165], s[76:77], 0, v[164:165]
	v_lshl_add_u64 v[164:165], v[164:165], 0, v[152:153]
	s_mov_b64 s[18:19], 0x80000
	s_and_b64 vcc, exec, s[4:5]
	s_mov_b32 s35, s12
	s_mov_b32 s34, s10
	s_mov_b64 s[20:21], s[14:15]
	s_waitcnt vmcnt(7)
	v_pk_fma_f32 v[144:145], v[144:145], v[80:81], v[184:185]
	v_pk_fma_f32 v[142:143], v[142:143], v[78:79], v[182:183]
	s_waitcnt vmcnt(6)
	v_pk_fma_f32 v[140:141], v[140:141], v[76:77], v[188:189]
	s_waitcnt vmcnt(4)
	v_pk_fma_f32 v[132:133], v[132:133], v[68:69], v[196:197]
	v_pk_fma_f32 v[130:131], v[130:131], v[66:67], v[194:195]
	global_store_dwordx4 v[158:159], v[130:133], off offset:576
	v_pk_fma_f32 v[138:139], v[138:139], v[74:75], v[186:187]
	v_pk_fma_f32 v[136:137], v[136:137], v[72:73], v[192:193]
	v_or_b32_e32 v130, 32, v154
	v_pk_fma_f32 v[134:135], v[134:135], v[70:71], v[190:191]
	v_ashrrev_i32_e32 v131, 31, v130
	global_store_dwordx4 v[158:159], v[142:145], off
	global_store_dwordx4 v[158:159], v[138:141], off offset:64
	global_store_dwordx4 v[158:159], v[134:137], off offset:512
	v_lshlrev_b64 v[158:159], 12, v[130:131]
	v_lshl_add_u64 v[130:131], s[78:79], 0, v[158:159]
	v_lshl_add_u64 v[130:131], v[130:131], 0, v[152:153]
	s_waitcnt vmcnt(4)
	v_pk_fma_f32 v[116:117], v[116:117], v[68:69], v[212:213]
	v_pk_fma_f32 v[114:115], v[114:115], v[66:67], v[210:211]
	global_load_dwordx4 v[142:145], v[130:131], off
	global_load_dwordx4 v[138:141], v[130:131], off offset:64
	global_load_dwordx4 v[134:137], v[130:131], off offset:512
	s_nop 0
	global_load_dwordx4 v[130:133], v[130:131], off offset:576
	v_pk_fma_f32 v[128:129], v[128:129], v[80:81], v[200:201]
	global_store_dwordx4 v[164:165], v[114:117], off offset:576
	v_pk_fma_f32 v[126:127], v[126:127], v[78:79], v[198:199]
	global_store_dwordx4 v[164:165], v[126:129], off
	v_or_b32_e32 v114, 48, v154
	v_ashrrev_i32_e32 v115, 31, v114
	v_lshlrev_b64 v[128:129], 12, v[114:115]
	v_pk_fma_f32 v[124:125], v[124:125], v[76:77], v[204:205]
	v_pk_fma_f32 v[122:123], v[122:123], v[74:75], v[202:203]
	v_pk_fma_f32 v[120:121], v[120:121], v[72:73], v[208:209]
	v_pk_fma_f32 v[118:119], v[118:119], v[70:71], v[206:207]
	v_lshl_add_u64 v[114:115], s[78:79], 0, v[128:129]
	global_store_dwordx4 v[164:165], v[122:125], off offset:64
	global_store_dwordx4 v[164:165], v[118:121], off offset:512
	v_lshl_add_u64 v[114:115], v[114:115], 0, v[152:153]
	global_load_dwordx4 v[116:119], v[114:115], off
	global_load_dwordx4 v[120:123], v[114:115], off offset:64
	global_load_dwordx4 v[124:127], v[114:115], off offset:512
	global_load_dwordx4 v[182:185], v[114:115], off offset:576
	v_lshl_add_u64 v[114:115], s[76:77], 0, v[158:159]
	v_lshl_add_u64 v[114:115], v[114:115], 0, v[152:153]
	s_waitcnt vmcnt(11)
	v_pk_fma_f32 v[112:113], v[112:113], v[80:81], v[144:145]
	v_pk_fma_f32 v[110:111], v[110:111], v[78:79], v[142:143]
	s_waitcnt vmcnt(10)
	v_pk_fma_f32 v[108:109], v[108:109], v[76:77], v[140:141]
	v_pk_fma_f32 v[106:107], v[106:107], v[74:75], v[138:139]
	s_waitcnt vmcnt(9)
	v_pk_fma_f32 v[96:97], v[96:97], v[72:73], v[136:137]
	v_pk_fma_f32 v[94:95], v[94:95], v[70:71], v[134:135]
	s_waitcnt vmcnt(8)
	v_pk_fma_f32 v[92:93], v[92:93], v[68:69], v[132:133]
	v_pk_fma_f32 v[90:91], v[90:91], v[66:67], v[130:131]
	global_store_dwordx4 v[114:115], v[110:113], off
	global_store_dwordx4 v[114:115], v[106:109], off offset:64
	global_store_dwordx4 v[114:115], v[94:97], off offset:512
	global_store_dwordx4 v[114:115], v[90:93], off offset:576
	v_lshl_add_u64 v[114:115], v[156:157], 0, s[18:19]
	s_mov_b64 s[18:19], s[16:17]
	v_lshl_add_u64 v[90:91], s[78:79], 0, v[114:115]
	v_lshl_add_u64 v[90:91], v[90:91], 0, v[152:153]
	s_waitcnt vmcnt(7)
	v_pk_fma_f32 v[102:103], v[102:103], v[78:79], v[116:117]
	v_lshl_add_u64 v[116:117], s[76:77], 0, v[128:129]
	v_lshl_add_u64 v[116:117], v[116:117], 0, v[152:153]
	s_waitcnt vmcnt(4)
	v_pk_fma_f32 v[84:85], v[84:85], v[68:69], v[184:185]
	v_pk_fma_f32 v[82:83], v[82:83], v[66:67], v[182:183]
	global_load_dwordx4 v[110:113], v[90:91], off
	global_load_dwordx4 v[106:109], v[90:91], off offset:64
	global_load_dwordx4 v[94:97], v[90:91], off offset:512
	s_nop 0
	global_load_dwordx4 v[90:93], v[90:91], off offset:576
	v_pk_fma_f32 v[104:105], v[104:105], v[80:81], v[118:119]
	global_store_dwordx4 v[116:117], v[82:85], off offset:576
	v_pk_fma_f32 v[100:101], v[100:101], v[76:77], v[122:123]
	v_pk_fma_f32 v[98:99], v[98:99], v[74:75], v[120:121]
	v_add_u32_e32 v82, 0x90, v154
	v_ashrrev_i32_e32 v83, 31, v82
	v_lshlrev_b64 v[84:85], 12, v[82:83]
	v_pk_fma_f32 v[88:89], v[88:89], v[72:73], v[126:127]
	v_pk_fma_f32 v[86:87], v[86:87], v[70:71], v[124:125]
	v_lshl_add_u64 v[82:83], s[78:79], 0, v[84:85]
	global_store_dwordx4 v[116:117], v[102:105], off
	global_store_dwordx4 v[116:117], v[98:101], off offset:64
	global_store_dwordx4 v[116:117], v[86:89], off offset:512
	v_lshl_add_u64 v[82:83], v[82:83], 0, v[152:153]
	global_load_dwordx4 v[86:89], v[82:83], off
	global_load_dwordx4 v[98:101], v[82:83], off offset:64
	global_load_dwordx4 v[102:105], v[82:83], off offset:512
	global_load_dwordx4 v[116:119], v[82:83], off offset:576
	v_lshl_add_u64 v[82:83], s[76:77], 0, v[114:115]
	v_lshl_add_u64 v[82:83], v[82:83], 0, v[152:153]
	v_lshl_add_u64 v[84:85], s[76:77], 0, v[84:85]
	v_lshl_add_u64 v[84:85], v[84:85], 0, v[152:153]
	s_waitcnt vmcnt(11)
	v_pk_fma_f32 v[64:65], v[64:65], v[80:81], v[112:113]
	v_pk_fma_f32 v[62:63], v[62:63], v[78:79], v[110:111]
	s_waitcnt vmcnt(10)
	v_pk_fma_f32 v[60:61], v[60:61], v[76:77], v[108:109]
	s_waitcnt vmcnt(8)
	v_pk_fma_f32 v[52:53], v[52:53], v[68:69], v[92:93]
	v_pk_fma_f32 v[50:51], v[50:51], v[66:67], v[90:91]
	global_store_dwordx4 v[82:83], v[50:53], off offset:576
	v_pk_fma_f32 v[58:59], v[58:59], v[74:75], v[106:107]
	v_pk_fma_f32 v[56:57], v[56:57], v[72:73], v[96:97]
	v_add_u32_e32 v50, 0xa0, v154
	v_pk_fma_f32 v[54:55], v[54:55], v[70:71], v[94:95]
	v_ashrrev_i32_e32 v51, 31, v50
	global_store_dwordx4 v[82:83], v[62:65], off
	global_store_dwordx4 v[82:83], v[58:61], off offset:64
	global_store_dwordx4 v[82:83], v[54:57], off offset:512
	v_lshlrev_b64 v[82:83], 12, v[50:51]
	v_lshl_add_u64 v[50:51], s[78:79], 0, v[82:83]
	v_lshl_add_u64 v[50:51], v[50:51], 0, v[152:153]
	global_load_dwordx4 v[62:65], v[50:51], off
	global_load_dwordx4 v[58:61], v[50:51], off offset:64
	global_load_dwordx4 v[54:57], v[50:51], off offset:512
	s_nop 0
	global_load_dwordx4 v[50:53], v[50:51], off offset:576
	s_waitcnt vmcnt(8)
	v_pk_fma_f32 v[36:37], v[36:37], v[68:69], v[118:119]
	v_pk_fma_f32 v[34:35], v[34:35], v[66:67], v[116:117]
	global_store_dwordx4 v[84:85], v[34:37], off offset:576
	v_pk_fma_f32 v[48:49], v[48:49], v[80:81], v[88:89]
	v_pk_fma_f32 v[46:47], v[46:47], v[78:79], v[86:87]
	v_add_u32_e32 v34, 0xb0, v154
	v_pk_fma_f32 v[44:45], v[44:45], v[76:77], v[100:101]
	v_pk_fma_f32 v[42:43], v[42:43], v[74:75], v[98:99]
	v_pk_fma_f32 v[40:41], v[40:41], v[72:73], v[104:105]
	v_pk_fma_f32 v[38:39], v[38:39], v[70:71], v[102:103]
	v_ashrrev_i32_e32 v35, 31, v34
	global_store_dwordx4 v[84:85], v[46:49], off
	global_store_dwordx4 v[84:85], v[42:45], off offset:64
	global_store_dwordx4 v[84:85], v[38:41], off offset:512
	v_lshlrev_b64 v[84:85], 12, v[34:35]
	v_lshl_add_u64 v[34:35], s[78:79], 0, v[84:85]
	v_lshl_add_u64 v[46:47], v[34:35], 0, v[152:153]
	global_load_dwordx4 v[34:37], v[46:47], off
	global_load_dwordx4 v[38:41], v[46:47], off offset:64
	global_load_dwordx4 v[42:45], v[46:47], off offset:512
	s_nop 0
	global_load_dwordx4 v[46:49], v[46:47], off offset:576
	s_waitcnt vmcnt(11)
	v_pk_fma_f32 v[30:31], v[30:31], v[78:79], v[62:63]
	v_lshl_add_u64 v[62:63], s[76:77], 0, v[82:83]
	v_lshl_add_u64 v[62:63], v[62:63], 0, v[152:153]
	s_waitcnt vmcnt(9)
	v_pk_fma_f32 v[16:17], v[16:17], v[72:73], v[56:57]
	v_pk_fma_f32 v[14:15], v[14:15], v[70:71], v[54:55]
	global_store_dwordx4 v[62:63], v[14:17], off offset:512
	s_waitcnt vmcnt(9)
	v_pk_fma_f32 v[12:13], v[12:13], v[68:69], v[52:53]
	v_pk_fma_f32 v[10:11], v[10:11], v[66:67], v[50:51]
	v_lshl_add_u64 v[14:15], s[76:77], 0, v[84:85]
	global_store_dwordx4 v[62:63], v[10:13], off offset:576
	v_lshl_add_u64 v[14:15], v[14:15], 0, v[152:153]
	v_pk_fma_f32 v[32:33], v[32:33], v[80:81], v[64:65]
	v_pk_fma_f32 v[28:29], v[28:29], v[76:77], v[60:61]
	v_pk_fma_f32 v[26:27], v[26:27], v[74:75], v[58:59]
	global_store_dwordx4 v[62:63], v[30:33], off
	global_store_dwordx4 v[62:63], v[26:29], off offset:64
	s_waitcnt vmcnt(7)
	v_pk_fma_f32 v[12:13], v[24:25], v[80:81], v[36:37]
	v_pk_fma_f32 v[10:11], v[22:23], v[78:79], v[34:35]
	global_store_dwordx4 v[14:15], v[10:13], off
	s_waitcnt vmcnt(6)
	v_pk_fma_f32 v[8:9], v[8:9], v[72:73], v[44:45]
	v_pk_fma_f32 v[6:7], v[6:7], v[70:71], v[42:43]
	v_pk_fma_f32 v[12:13], v[20:21], v[76:77], v[40:41]
	v_pk_fma_f32 v[10:11], v[18:19], v[74:75], v[38:39]
	s_waitcnt vmcnt(5)
	v_pk_fma_f32 v[4:5], v[4:5], v[68:69], v[48:49]
	v_pk_fma_f32 v[2:3], v[2:3], v[66:67], v[46:47]
	global_store_dwordx4 v[14:15], v[10:13], off offset:64
	global_store_dwordx4 v[14:15], v[6:9], off offset:512
	global_store_dwordx4 v[14:15], v[2:5], off offset:576
	s_cbranch_vccz .LBB0_89
	s_waitcnt vmcnt(0)
	s_cmpk_gt_u32 s2, 0xff
	s_cbranch_scc1 .LBB0_96
	s_barrier

.LBB0_895:
	s_add_u32 s14, s12, 0x100
	s_addc_u32 s15, s13, 0
	s_add_i32 s39, 0, 0x10000
	v_add_u32_e32 v78, s39, v159
	ds_read_b128 v[66:69], v78
	ds_read_b128 v[70:73], v78 offset:1024
	ds_read_b128 v[74:77], v78 offset:2048
	ds_read_b128 v[78:81], v78 offset:3072
	s_cmp_eq_u32 s38, 40
	s_cselect_b32 s19, s1, s15
	s_cselect_b32 s18, s0, s14
	s_cselect_b32 s17, s7, s37
	s_cselect_b32 s16, s6, s36
	v_lshl_add_u64 v[156:157], s[12:13], 0, v[150:151]
	s_add_i32 m0, s23, 0xc000
	ds_read_b128 v[152:155], v161
	ds_read_b128 v[162:165], v161 offset:1024
	ds_read_b128 v[182:185], v161 offset:2048
	ds_read_b128 v[186:189], v161 offset:3072
	ds_read_b128 v[190:193], v161 offset:4096
	ds_read_b128 v[194:197], v161 offset:5120
	ds_read_b128 v[198:201], v161 offset:6144
	ds_read_b128 v[202:205], v161 offset:7168
	global_load_lds_dwordx4 v[156:157], off
	v_lshl_add_u64 v[156:157], s[12:13], 0, v[148:149]
	s_add_i32 m0, s23, 0xe000
	s_nop 0
	global_load_lds_dwordx4 v[156:157], off
	s_waitcnt lgkmcnt(8)
	s_barrier
	s_waitcnt lgkmcnt(0)
	s_setprio 1
	s_waitcnt lgkmcnt(0)
	v_mfma_f32_16x16x32_bf16 v[142:145], v[66:69], v[152:155], v[142:145]
	v_mfma_f32_16x16x32_bf16 v[138:141], v[74:77], v[152:155], v[138:141]
	v_mfma_f32_16x16x32_bf16 v[126:129], v[66:69], v[182:185], v[126:129]
	v_mfma_f32_16x16x32_bf16 v[122:125], v[74:77], v[182:185], v[122:125]
	v_mfma_f32_16x16x32_bf16 v[118:121], v[66:69], v[190:193], v[118:121]
	v_mfma_f32_16x16x32_bf16 v[114:117], v[74:77], v[190:193], v[114:117]
	v_mfma_f32_16x16x32_bf16 v[94:97], v[66:69], v[198:201], v[94:97]
	v_mfma_f32_16x16x32_bf16 v[90:93], v[74:77], v[198:201], v[90:93]
	v_mfma_f32_16x16x32_bf16 v[142:145], v[70:73], v[162:165], v[142:145]
	v_mfma_f32_16x16x32_bf16 v[138:141], v[78:81], v[162:165], v[138:141]
	v_mfma_f32_16x16x32_bf16 v[126:129], v[70:73], v[186:189], v[126:129]
	v_mfma_f32_16x16x32_bf16 v[122:125], v[78:81], v[186:189], v[122:125]
	v_mfma_f32_16x16x32_bf16 v[118:121], v[70:73], v[194:197], v[118:121]
	v_mfma_f32_16x16x32_bf16 v[114:117], v[78:81], v[194:197], v[114:117]
	v_mfma_f32_16x16x32_bf16 v[94:97], v[70:73], v[202:205], v[94:97]
	v_mfma_f32_16x16x32_bf16 v[90:93], v[78:81], v[202:205], v[90:93]
	s_setprio 0
	s_barrier
	s_add_i32 s60, 0, 0x14000
	v_add_u32_e32 v156, s60, v159
	s_add_i32 s12, s39, s22
	ds_read_b128 v[206:209], v156
	ds_read_b128 v[210:213], v156 offset:1024
	ds_read_b128 v[230:233], v156 offset:2048
	ds_read_b128 v[234:237], v156 offset:3072
	v_lshl_add_u64 v[156:157], s[16:17], 0, v[0:1]
	s_mov_b32 m0, s12
	v_lshl_add_u64 v[228:229], s[16:17], 0, v[146:147]
	global_load_lds_dwordx4 v[156:157], off
	s_add_i32 m0, s12, 0x2000
	s_nop 0
	global_load_lds_dwordx4 v[228:229], off
	s_barrier
	s_waitcnt lgkmcnt(0)
	s_setprio 1
	s_waitcnt lgkmcnt(0)
	v_mfma_f32_16x16x32_bf16 v[134:137], v[206:209], v[152:155], v[134:137]
	v_mfma_f32_16x16x32_bf16 v[130:133], v[230:233], v[152:155], v[130:133]
	v_mfma_f32_16x16x32_bf16 v[110:113], v[206:209], v[182:185], v[110:113]
	v_mfma_f32_16x16x32_bf16 v[106:109], v[230:233], v[182:185], v[106:109]
	v_mfma_f32_16x16x32_bf16 v[102:105], v[206:209], v[190:193], v[102:105]
	v_mfma_f32_16x16x32_bf16 v[98:101], v[230:233], v[190:193], v[98:101]
	v_mfma_f32_16x16x32_bf16 v[86:89], v[206:209], v[198:201], v[86:89]
	v_mfma_f32_16x16x32_bf16 v[82:85], v[230:233], v[198:201], v[82:85]
	v_mfma_f32_16x16x32_bf16 v[134:137], v[210:213], v[162:165], v[134:137]
	v_mfma_f32_16x16x32_bf16 v[130:133], v[234:237], v[162:165], v[130:133]
	v_mfma_f32_16x16x32_bf16 v[110:113], v[210:213], v[186:189], v[110:113]
	v_mfma_f32_16x16x32_bf16 v[106:109], v[234:237], v[186:189], v[106:109]
	v_mfma_f32_16x16x32_bf16 v[102:105], v[210:213], v[194:197], v[102:105]
	v_mfma_f32_16x16x32_bf16 v[98:101], v[234:237], v[194:197], v[98:101]
	v_mfma_f32_16x16x32_bf16 v[86:89], v[210:213], v[202:205], v[86:89]
	v_mfma_f32_16x16x32_bf16 v[82:85], v[234:237], v[202:205], v[82:85]
	s_setprio 0
	s_mov_b32 m0, s23
	v_lshl_add_u64 v[238:239], s[18:19], 0, v[0:1]
	s_barrier
	ds_read_b128 v[152:155], v161 offset:16384
	ds_read_b128 v[162:165], v161 offset:17408
	ds_read_b128 v[182:185], v161 offset:18432
	ds_read_b128 v[186:189], v161 offset:19456
	ds_read_b128 v[190:193], v161 offset:20480
	ds_read_b128 v[194:197], v161 offset:21504
	ds_read_b128 v[198:201], v161 offset:22528
	ds_read_b128 v[202:205], v161 offset:23552
	global_load_lds_dwordx4 v[238:239], off
	v_lshl_add_u64 v[240:241], s[18:19], 0, v[146:147]
	s_mov_b32 m0, s24
	s_nop 0
	global_load_lds_dwordx4 v[240:241], off
	s_barrier
	s_waitcnt lgkmcnt(0)
	s_setprio 1
	s_waitcnt lgkmcnt(0)
	v_mfma_f32_16x16x32_bf16 v[62:65], v[66:69], v[152:155], v[62:65]
	v_mfma_f32_16x16x32_bf16 v[58:61], v[74:77], v[152:155], v[58:61]
	v_mfma_f32_16x16x32_bf16 v[46:49], v[66:69], v[182:185], v[46:49]
	v_mfma_f32_16x16x32_bf16 v[42:45], v[74:77], v[182:185], v[42:45]
	v_mfma_f32_16x16x32_bf16 v[30:33], v[66:69], v[190:193], v[30:33]
	v_mfma_f32_16x16x32_bf16 v[26:29], v[74:77], v[190:193], v[26:29]
	v_mfma_f32_16x16x32_bf16 v[22:25], v[66:69], v[198:201], v[22:25]
	v_mfma_f32_16x16x32_bf16 v[14:17], v[74:77], v[198:201], v[14:17]
	v_mfma_f32_16x16x32_bf16 v[62:65], v[70:73], v[162:165], v[62:65]
	v_mfma_f32_16x16x32_bf16 v[58:61], v[78:81], v[162:165], v[58:61]
	v_mfma_f32_16x16x32_bf16 v[46:49], v[70:73], v[186:189], v[46:49]
	v_mfma_f32_16x16x32_bf16 v[42:45], v[78:81], v[186:189], v[42:45]
	v_mfma_f32_16x16x32_bf16 v[30:33], v[70:73], v[194:197], v[30:33]
	v_mfma_f32_16x16x32_bf16 v[26:29], v[78:81], v[194:197], v[26:29]
	v_mfma_f32_16x16x32_bf16 v[22:25], v[70:73], v[202:205], v[22:25]
	v_mfma_f32_16x16x32_bf16 v[14:17], v[78:81], v[202:205], v[14:17]
	s_setprio 0
	s_barrier
	s_add_u32 s12, s16, 0xb0000
	s_addc_u32 s13, s17, 0
	s_add_i32 s39, s60, s22
	v_lshl_add_u64 v[66:67], s[12:13], 0, v[0:1]
	s_mov_b32 m0, s39
	s_nop 0
	global_load_lds_dwordx4 v[66:67], off
	v_lshl_add_u64 v[66:67], s[12:13], 0, v[146:147]
	s_add_i32 m0, s39, 0x2000
	s_nop 0
	global_load_lds_dwordx4 v[66:67], off
	s_waitcnt vmcnt(6)
	s_barrier
	s_setprio 1
	v_mfma_f32_16x16x32_bf16 v[54:57], v[206:209], v[152:155], v[54:57]
	v_mfma_f32_16x16x32_bf16 v[50:53], v[230:233], v[152:155], v[50:53]
	v_mfma_f32_16x16x32_bf16 v[38:41], v[206:209], v[182:185], v[38:41]
	v_mfma_f32_16x16x32_bf16 v[34:37], v[230:233], v[182:185], v[34:37]
	v_mfma_f32_16x16x32_bf16 v[18:21], v[206:209], v[190:193], v[18:21]
	v_mfma_f32_16x16x32_bf16 v[10:13], v[230:233], v[190:193], v[10:13]
	v_mfma_f32_16x16x32_bf16 v[6:9], v[206:209], v[198:201], v[6:9]
	v_mfma_f32_16x16x32_bf16 v[2:5], v[230:233], v[198:201], v[2:5]
	v_mfma_f32_16x16x32_bf16 v[54:57], v[210:213], v[162:165], v[54:57]
	v_mfma_f32_16x16x32_bf16 v[50:53], v[234:237], v[162:165], v[50:53]
	v_mfma_f32_16x16x32_bf16 v[38:41], v[210:213], v[186:189], v[38:41]
	v_mfma_f32_16x16x32_bf16 v[34:37], v[234:237], v[186:189], v[34:37]
	v_mfma_f32_16x16x32_bf16 v[18:21], v[210:213], v[194:197], v[18:21]
	v_mfma_f32_16x16x32_bf16 v[10:13], v[234:237], v[194:197], v[10:13]
	v_mfma_f32_16x16x32_bf16 v[6:9], v[210:213], v[202:205], v[6:9]
	v_mfma_f32_16x16x32_bf16 v[2:5], v[234:237], v[202:205], v[2:5]
	s_setprio 0
	s_add_i32 s39, 0, 0x18000
	v_add_u32_e32 v78, s39, v159
	s_barrier
	ds_read_b128 v[66:69], v78
	ds_read_b128 v[70:73], v78 offset:1024
	ds_read_b128 v[74:77], v78 offset:2048
	ds_read_b128 v[78:81], v78 offset:3072
	s_add_u32 s12, s18, 0xb0000
	s_addc_u32 s13, s19, 0
	s_mov_b32 m0, s25
	v_lshl_add_u64 v[206:207], s[12:13], 0, v[0:1]
	ds_read_b128 v[152:155], v161 offset:32768
	ds_read_b128 v[162:165], v161 offset:33792
	ds_read_b128 v[182:185], v161 offset:34816
	ds_read_b128 v[186:189], v161 offset:35840
	ds_read_b128 v[190:193], v161 offset:36864
	ds_read_b128 v[194:197], v161 offset:37888
	ds_read_b128 v[198:201], v161 offset:38912
	ds_read_b128 v[202:205], v161 offset:39936
	global_load_lds_dwordx4 v[206:207], off
	v_lshl_add_u64 v[206:207], s[12:13], 0, v[146:147]
	s_mov_b32 m0, s26
	s_nop 0
	global_load_lds_dwordx4 v[206:207], off
	s_waitcnt lgkmcnt(8)
	s_barrier
	s_waitcnt lgkmcnt(0)
	s_setprio 1
	s_waitcnt lgkmcnt(0)
	v_mfma_f32_16x16x32_bf16 v[142:145], v[66:69], v[152:155], v[142:145]
	v_mfma_f32_16x16x32_bf16 v[138:141], v[74:77], v[152:155], v[138:141]
	v_mfma_f32_16x16x32_bf16 v[126:129], v[66:69], v[182:185], v[126:129]
	v_mfma_f32_16x16x32_bf16 v[122:125], v[74:77], v[182:185], v[122:125]
	v_mfma_f32_16x16x32_bf16 v[118:121], v[66:69], v[190:193], v[118:121]
	v_mfma_f32_16x16x32_bf16 v[114:117], v[74:77], v[190:193], v[114:117]
	v_mfma_f32_16x16x32_bf16 v[94:97], v[66:69], v[198:201], v[94:97]
	v_mfma_f32_16x16x32_bf16 v[90:93], v[74:77], v[198:201], v[90:93]
	v_mfma_f32_16x16x32_bf16 v[142:145], v[70:73], v[162:165], v[142:145]
	v_mfma_f32_16x16x32_bf16 v[138:141], v[78:81], v[162:165], v[138:141]
	v_mfma_f32_16x16x32_bf16 v[126:129], v[70:73], v[186:189], v[126:129]
	v_mfma_f32_16x16x32_bf16 v[122:125], v[78:81], v[186:189], v[122:125]
	v_mfma_f32_16x16x32_bf16 v[118:121], v[70:73], v[194:197], v[118:121]
	v_mfma_f32_16x16x32_bf16 v[114:117], v[78:81], v[194:197], v[114:117]
	v_mfma_f32_16x16x32_bf16 v[94:97], v[70:73], v[202:205], v[94:97]
	v_mfma_f32_16x16x32_bf16 v[90:93], v[78:81], v[202:205], v[90:93]
	s_setprio 0
	s_barrier
	s_add_i32 s18, 0, 0x1c000
	s_add_i32 s12, s39, s22
	v_add_u32_e32 v169, s18, v159
	v_lshl_add_u64 v[156:157], v[156:157], 0, s[94:95]
	s_mov_b32 m0, s12
	ds_read_b128 v[206:209], v169
	ds_read_b128 v[210:213], v169 offset:1024
	ds_read_b128 v[230:233], v169 offset:2048
	ds_read_b128 v[234:237], v169 offset:3072
	global_load_lds_dwordx4 v[156:157], off
	v_lshl_add_u64 v[156:157], v[228:229], 0, s[94:95]
	s_add_i32 m0, s12, 0x2000
	s_nop 0
	global_load_lds_dwordx4 v[156:157], off
	s_barrier
	s_waitcnt lgkmcnt(0)
	s_setprio 1
	s_waitcnt lgkmcnt(0)
	v_mfma_f32_16x16x32_bf16 v[134:137], v[206:209], v[152:155], v[134:137]
	v_mfma_f32_16x16x32_bf16 v[130:133], v[230:233], v[152:155], v[130:133]
	v_mfma_f32_16x16x32_bf16 v[110:113], v[206:209], v[182:185], v[110:113]
	v_mfma_f32_16x16x32_bf16 v[106:109], v[230:233], v[182:185], v[106:109]
	v_mfma_f32_16x16x32_bf16 v[102:105], v[206:209], v[190:193], v[102:105]
	v_mfma_f32_16x16x32_bf16 v[98:101], v[230:233], v[190:193], v[98:101]
	v_mfma_f32_16x16x32_bf16 v[86:89], v[206:209], v[198:201], v[86:89]
	v_mfma_f32_16x16x32_bf16 v[82:85], v[230:233], v[198:201], v[82:85]
	v_mfma_f32_16x16x32_bf16 v[134:137], v[210:213], v[162:165], v[134:137]
	v_mfma_f32_16x16x32_bf16 v[130:133], v[234:237], v[162:165], v[130:133]
	v_mfma_f32_16x16x32_bf16 v[110:113], v[210:213], v[186:189], v[110:113]
	v_mfma_f32_16x16x32_bf16 v[106:109], v[234:237], v[186:189], v[106:109]
	v_mfma_f32_16x16x32_bf16 v[102:105], v[210:213], v[194:197], v[102:105]
	v_mfma_f32_16x16x32_bf16 v[98:101], v[234:237], v[194:197], v[98:101]
	v_mfma_f32_16x16x32_bf16 v[86:89], v[210:213], v[202:205], v[86:89]
	v_mfma_f32_16x16x32_bf16 v[82:85], v[234:237], v[202:205], v[82:85]
	s_setprio 0
	s_mov_b32 m0, s27
	v_lshl_add_u64 v[156:157], v[238:239], 0, s[94:95]
	s_barrier
	ds_read_b128 v[152:155], v161 offset:49152
	ds_read_b128 v[162:165], v161 offset:50176
	ds_read_b128 v[182:185], v161 offset:51200
	ds_read_b128 v[186:189], v161 offset:52224
	ds_read_b128 v[190:193], v161 offset:53248
	ds_read_b128 v[194:197], v161 offset:54272
	ds_read_b128 v[198:201], v161 offset:55296
	ds_read_b128 v[202:205], v161 offset:56320
	global_load_lds_dwordx4 v[156:157], off
	v_lshl_add_u64 v[156:157], v[240:241], 0, s[94:95]
	s_mov_b32 m0, s28
	s_nop 0
	global_load_lds_dwordx4 v[156:157], off
	s_barrier
	s_waitcnt lgkmcnt(0)
	s_setprio 1
	s_waitcnt lgkmcnt(0)
	v_mfma_f32_16x16x32_bf16 v[62:65], v[66:69], v[152:155], v[62:65]
	v_mfma_f32_16x16x32_bf16 v[58:61], v[74:77], v[152:155], v[58:61]
	v_mfma_f32_16x16x32_bf16 v[46:49], v[66:69], v[182:185], v[46:49]
	v_mfma_f32_16x16x32_bf16 v[42:45], v[74:77], v[182:185], v[42:45]
	v_mfma_f32_16x16x32_bf16 v[30:33], v[66:69], v[190:193], v[30:33]
	v_mfma_f32_16x16x32_bf16 v[26:29], v[74:77], v[190:193], v[26:29]
	v_mfma_f32_16x16x32_bf16 v[22:25], v[66:69], v[198:201], v[22:25]
	v_mfma_f32_16x16x32_bf16 v[14:17], v[74:77], v[198:201], v[14:17]
	v_mfma_f32_16x16x32_bf16 v[62:65], v[70:73], v[162:165], v[62:65]
	v_mfma_f32_16x16x32_bf16 v[58:61], v[78:81], v[162:165], v[58:61]
	v_mfma_f32_16x16x32_bf16 v[46:49], v[70:73], v[186:189], v[46:49]
	v_mfma_f32_16x16x32_bf16 v[42:45], v[78:81], v[186:189], v[42:45]
	v_mfma_f32_16x16x32_bf16 v[30:33], v[70:73], v[194:197], v[30:33]
	v_mfma_f32_16x16x32_bf16 v[26:29], v[78:81], v[194:197], v[26:29]
	v_mfma_f32_16x16x32_bf16 v[22:25], v[70:73], v[202:205], v[22:25]
	v_mfma_f32_16x16x32_bf16 v[14:17], v[78:81], v[202:205], v[14:17]
	s_setprio 0
	s_barrier
	s_add_u32 s12, s16, 0xb0080
	s_addc_u32 s13, s17, 0
	s_add_i32 s16, s18, s22
	v_lshl_add_u64 v[66:67], s[12:13], 0, v[0:1]
	s_mov_b32 m0, s16
	s_nop 0
	global_load_lds_dwordx4 v[66:67], off
	v_lshl_add_u64 v[66:67], s[12:13], 0, v[146:147]
	s_add_i32 m0, s16, 0x2000
	s_nop 0
	global_load_lds_dwordx4 v[66:67], off
	s_waitcnt vmcnt(6)
	s_barrier
	s_setprio 1
	v_mfma_f32_16x16x32_bf16 v[54:57], v[206:209], v[152:155], v[54:57]
	v_mfma_f32_16x16x32_bf16 v[50:53], v[230:233], v[152:155], v[50:53]
	v_mfma_f32_16x16x32_bf16 v[38:41], v[206:209], v[182:185], v[38:41]
	v_mfma_f32_16x16x32_bf16 v[34:37], v[230:233], v[182:185], v[34:37]
	v_mfma_f32_16x16x32_bf16 v[18:21], v[206:209], v[190:193], v[18:21]
	v_mfma_f32_16x16x32_bf16 v[10:13], v[230:233], v[190:193], v[10:13]
	v_mfma_f32_16x16x32_bf16 v[6:9], v[206:209], v[198:201], v[6:9]
	v_mfma_f32_16x16x32_bf16 v[2:5], v[230:233], v[198:201], v[2:5]
	v_mfma_f32_16x16x32_bf16 v[54:57], v[210:213], v[162:165], v[54:57]
	v_mfma_f32_16x16x32_bf16 v[50:53], v[234:237], v[162:165], v[50:53]
	v_mfma_f32_16x16x32_bf16 v[38:41], v[210:213], v[186:189], v[38:41]
	v_mfma_f32_16x16x32_bf16 v[34:37], v[234:237], v[186:189], v[34:37]
	v_mfma_f32_16x16x32_bf16 v[18:21], v[210:213], v[194:197], v[18:21]
	v_mfma_f32_16x16x32_bf16 v[10:13], v[234:237], v[194:197], v[10:13]
	v_mfma_f32_16x16x32_bf16 v[6:9], v[210:213], v[202:205], v[6:9]
	v_mfma_f32_16x16x32_bf16 v[2:5], v[234:237], v[202:205], v[2:5]
	s_setprio 0
	s_add_i32 s38, s38, 2
	s_add_u32 s36, s36, 0x100
	s_addc_u32 s37, s37, 0
	s_cmp_gt_u32 s38, 41
	s_mov_b64 s[12:13], s[14:15]
	s_barrier
	s_cbranch_scc0 .LBB0_895
	s_ashr_i32 s12, s34, 4
	v_lshl_add_u32 v154, s34, 8, v158
	s_mul_hi_i32 s13, s12, 0x6000
	s_mulk_i32 s12, 0x6000
	v_lshl_or_b32 v66, s35, 8, v160
	v_ashrrev_i32_e32 v155, 31, v154
	s_add_u32 s12, s8, s12
	v_ashrrev_i32_e32 v67, 31, v66
	v_lshlrev_b64 v[156:157], 12, v[154:155]
	s_addc_u32 s13, s9, s13
	v_lshlrev_b64 v[152:153], 2, v[66:67]
	v_lshl_add_u64 v[156:157], s[76:77], 0, v[156:157]
	v_lshl_add_u64 v[66:67], s[12:13], 0, v[152:153]
	v_lshl_add_u64 v[156:157], v[156:157], 0, v[152:153]
	global_load_dwordx4 v[78:81], v[66:67], off
	global_load_dwordx4 v[74:77], v[66:67], off offset:64
	global_load_dwordx4 v[70:73], v[66:67], off offset:512
	s_nop 0
	global_load_dwordx4 v[66:69], v[66:67], off offset:576
	s_nop 0
	global_load_dwordx4 v[162:165], v[156:157], off
	global_load_dwordx4 v[182:185], v[156:157], off offset:64
	global_load_dwordx4 v[186:189], v[156:157], off offset:512
	global_load_dwordx4 v[190:193], v[156:157], off offset:576
	v_or_b32_e32 v194, 16, v154
	v_ashrrev_i32_e32 v195, 31, v194
	v_lshlrev_b64 v[194:195], 12, v[194:195]
	v_lshl_add_u64 v[194:195], s[76:77], 0, v[194:195]
	v_lshl_add_u64 v[210:211], v[194:195], 0, v[152:153]
	global_load_dwordx4 v[194:197], v[210:211], off
	global_load_dwordx4 v[198:201], v[210:211], off offset:64
	global_load_dwordx4 v[202:205], v[210:211], off offset:512
	global_load_dwordx4 v[206:209], v[210:211], off offset:576
	s_mov_b64 s[12:13], 0x80000
	s_mov_b32 s35, s30
	s_mov_b32 s34, s31
	s_mov_b64 s[14:15], s[6:7]
	s_waitcnt vmcnt(7)
	v_pk_fma_f32 v[144:145], v[144:145], v[80:81], v[164:165]
	v_pk_fma_f32 v[142:143], v[142:143], v[78:79], v[162:163]
	s_waitcnt vmcnt(6)
	v_pk_fma_f32 v[140:141], v[140:141], v[76:77], v[184:185]
	s_waitcnt vmcnt(4)
	v_pk_fma_f32 v[132:133], v[132:133], v[68:69], v[192:193]
	v_pk_fma_f32 v[130:131], v[130:131], v[66:67], v[190:191]
	global_store_dwordx4 v[156:157], v[130:133], off offset:576
	v_pk_fma_f32 v[138:139], v[138:139], v[74:75], v[182:183]
	v_pk_fma_f32 v[136:137], v[136:137], v[72:73], v[188:189]
	v_or_b32_e32 v130, 32, v154
	v_ashrrev_i32_e32 v131, 31, v130
	v_lshlrev_b64 v[130:131], 12, v[130:131]
	v_pk_fma_f32 v[134:135], v[134:135], v[70:71], v[186:187]
	v_lshl_add_u64 v[130:131], s[76:77], 0, v[130:131]
	global_store_dwordx4 v[156:157], v[142:145], off
	global_store_dwordx4 v[156:157], v[138:141], off offset:64
	global_store_dwordx4 v[156:157], v[134:137], off offset:512
	v_lshl_add_u64 v[162:163], v[130:131], 0, v[152:153]
	s_waitcnt vmcnt(4)
	v_pk_fma_f32 v[108:109], v[108:109], v[68:69], v[208:209]
	v_pk_fma_f32 v[106:107], v[106:107], v[66:67], v[206:207]
	global_load_dwordx4 v[130:133], v[162:163], off
	global_load_dwordx4 v[134:137], v[162:163], off offset:64
	global_load_dwordx4 v[138:141], v[162:163], off offset:512
	global_load_dwordx4 v[142:145], v[162:163], off offset:576
	v_pk_fma_f32 v[128:129], v[128:129], v[80:81], v[196:197]
	global_store_dwordx4 v[210:211], v[106:109], off offset:576
	v_pk_fma_f32 v[126:127], v[126:127], v[78:79], v[194:195]
	v_pk_fma_f32 v[124:125], v[124:125], v[76:77], v[200:201]
	v_or_b32_e32 v106, 48, v154
	v_ashrrev_i32_e32 v107, 31, v106
	v_lshlrev_b64 v[106:107], 12, v[106:107]
	v_pk_fma_f32 v[122:123], v[122:123], v[74:75], v[198:199]
	v_pk_fma_f32 v[112:113], v[112:113], v[72:73], v[204:205]
	v_pk_fma_f32 v[110:111], v[110:111], v[70:71], v[202:203]
	v_lshl_add_u64 v[106:107], s[76:77], 0, v[106:107]
	global_store_dwordx4 v[210:211], v[126:129], off
	global_store_dwordx4 v[210:211], v[122:125], off offset:64
	global_store_dwordx4 v[210:211], v[110:113], off offset:512
	v_lshl_add_u64 v[164:165], v[106:107], 0, v[152:153]
	global_load_dwordx4 v[106:109], v[164:165], off
	global_load_dwordx4 v[110:113], v[164:165], off offset:64
	global_load_dwordx4 v[122:125], v[164:165], off offset:512
	global_load_dwordx4 v[126:129], v[164:165], off offset:576
	s_waitcnt vmcnt(11)
	v_pk_fma_f32 v[120:121], v[120:121], v[80:81], v[132:133]
	v_pk_fma_f32 v[118:119], v[118:119], v[78:79], v[130:131]
	s_waitcnt vmcnt(10)
	v_pk_fma_f32 v[116:117], v[116:117], v[76:77], v[136:137]
	s_waitcnt vmcnt(8)
	v_pk_fma_f32 v[100:101], v[100:101], v[68:69], v[144:145]
	v_pk_fma_f32 v[98:99], v[98:99], v[66:67], v[142:143]
	global_store_dwordx4 v[162:163], v[98:101], off offset:576
	v_pk_fma_f32 v[114:115], v[114:115], v[74:75], v[134:135]
	v_pk_fma_f32 v[104:105], v[104:105], v[72:73], v[140:141]
	v_lshl_add_u64 v[98:99], v[156:157], 0, s[12:13]
	s_mov_b32 s12, 0x80000
	v_pk_fma_f32 v[102:103], v[102:103], v[70:71], v[138:139]
	v_add_co_u32_e32 v134, vcc, s12, v156
	global_store_dwordx4 v[162:163], v[118:121], off
	global_store_dwordx4 v[162:163], v[114:117], off offset:64
	global_store_dwordx4 v[162:163], v[102:105], off offset:512
	v_addc_co_u32_e32 v135, vcc, 0, v157, vcc
	global_load_dwordx4 v[102:105], v[134:135], off
	global_load_dwordx4 v[114:117], v[98:99], off offset:64
	global_load_dwordx4 v[118:121], v[98:99], off offset:512
	global_load_dwordx4 v[130:133], v[98:99], off offset:576
	s_waitcnt vmcnt(8)
	v_pk_fma_f32 v[84:85], v[84:85], v[68:69], v[128:129]
	v_pk_fma_f32 v[82:83], v[82:83], v[66:67], v[126:127]
	global_store_dwordx4 v[164:165], v[82:85], off offset:576
	v_pk_fma_f32 v[96:97], v[96:97], v[80:81], v[108:109]
	v_pk_fma_f32 v[94:95], v[94:95], v[78:79], v[106:107]
	v_add_u32_e32 v82, 0x90, v154
	v_ashrrev_i32_e32 v83, 31, v82
	v_lshlrev_b64 v[82:83], 12, v[82:83]
	v_pk_fma_f32 v[92:93], v[92:93], v[76:77], v[112:113]
	v_pk_fma_f32 v[90:91], v[90:91], v[74:75], v[110:111]
	v_pk_fma_f32 v[88:89], v[88:89], v[72:73], v[124:125]
	v_pk_fma_f32 v[86:87], v[86:87], v[70:71], v[122:123]
	v_lshl_add_u64 v[82:83], s[76:77], 0, v[82:83]
	global_store_dwordx4 v[164:165], v[94:97], off
	global_store_dwordx4 v[164:165], v[90:93], off offset:64
	global_store_dwordx4 v[164:165], v[86:89], off offset:512
	v_lshl_add_u64 v[100:101], v[82:83], 0, v[152:153]
	global_load_dwordx4 v[94:97], v[100:101], off
	global_load_dwordx4 v[90:93], v[100:101], off offset:64
	global_load_dwordx4 v[86:89], v[100:101], off offset:512
	global_load_dwordx4 v[82:85], v[100:101], off offset:576
	s_and_b64 vcc, exec, s[4:5]
	s_mov_b64 s[12:13], s[0:1]
	s_waitcnt vmcnt(11)
	v_pk_fma_f32 v[64:65], v[64:65], v[80:81], v[104:105]
	v_pk_fma_f32 v[62:63], v[62:63], v[78:79], v[102:103]
	s_waitcnt vmcnt(10)
	v_pk_fma_f32 v[60:61], v[60:61], v[76:77], v[116:117]
	s_waitcnt vmcnt(8)
	v_pk_fma_f32 v[52:53], v[52:53], v[68:69], v[132:133]
	v_pk_fma_f32 v[50:51], v[50:51], v[66:67], v[130:131]
	global_store_dwordx4 v[98:99], v[50:53], off offset:576
	v_pk_fma_f32 v[58:59], v[58:59], v[74:75], v[114:115]
	v_pk_fma_f32 v[56:57], v[56:57], v[72:73], v[120:121]
	v_add_u32_e32 v50, 0xa0, v154
	v_ashrrev_i32_e32 v51, 31, v50
	v_lshlrev_b64 v[50:51], 12, v[50:51]
	v_pk_fma_f32 v[54:55], v[54:55], v[70:71], v[118:119]
	v_lshl_add_u64 v[50:51], s[76:77], 0, v[50:51]
	global_store_dwordx4 v[134:135], v[62:65], off
	global_store_dwordx4 v[98:99], v[58:61], off offset:64
	global_store_dwordx4 v[98:99], v[54:57], off offset:512
	v_lshl_add_u64 v[98:99], v[50:51], 0, v[152:153]
	global_load_dwordx4 v[62:65], v[98:99], off
	global_load_dwordx4 v[54:57], v[98:99], off offset:64
	global_load_dwordx4 v[58:61], v[98:99], off offset:512
	global_load_dwordx4 v[50:53], v[98:99], off offset:576
	s_waitcnt vmcnt(11)
	v_pk_fma_f32 v[48:49], v[48:49], v[80:81], v[96:97]
	v_pk_fma_f32 v[46:47], v[46:47], v[78:79], v[94:95]
	s_waitcnt vmcnt(10)
	v_pk_fma_f32 v[44:45], v[44:45], v[76:77], v[92:93]
	s_waitcnt vmcnt(8)
	v_pk_fma_f32 v[36:37], v[36:37], v[68:69], v[84:85]
	v_pk_fma_f32 v[34:35], v[34:35], v[66:67], v[82:83]
	global_store_dwordx4 v[100:101], v[34:37], off offset:576
	v_pk_fma_f32 v[42:43], v[42:43], v[74:75], v[90:91]
	v_pk_fma_f32 v[40:41], v[40:41], v[72:73], v[88:89]
	v_add_u32_e32 v34, 0xb0, v154
	v_ashrrev_i32_e32 v35, 31, v34
	v_lshlrev_b64 v[34:35], 12, v[34:35]
	v_pk_fma_f32 v[38:39], v[38:39], v[70:71], v[86:87]
	v_lshl_add_u64 v[34:35], s[76:77], 0, v[34:35]
	global_store_dwordx4 v[100:101], v[46:49], off
	global_store_dwordx4 v[100:101], v[42:45], off offset:64
	global_store_dwordx4 v[100:101], v[38:41], off offset:512
	v_lshl_add_u64 v[82:83], v[34:35], 0, v[152:153]
	global_load_dwordx4 v[46:49], v[82:83], off
	global_load_dwordx4 v[42:45], v[82:83], off offset:64
	global_load_dwordx4 v[38:41], v[82:83], off offset:512
	global_load_dwordx4 v[34:37], v[82:83], off offset:576
	s_waitcnt vmcnt(11)
	v_pk_fma_f32 v[32:33], v[32:33], v[80:81], v[64:65]
	v_pk_fma_f32 v[30:31], v[30:31], v[78:79], v[62:63]
	s_waitcnt vmcnt(10)
	v_pk_fma_f32 v[28:29], v[28:29], v[76:77], v[56:57]
	s_waitcnt vmcnt(8)
	v_pk_fma_f32 v[12:13], v[12:13], v[68:69], v[52:53]
	v_pk_fma_f32 v[10:11], v[10:11], v[66:67], v[50:51]
	global_store_dwordx4 v[98:99], v[10:13], off offset:576
	v_pk_fma_f32 v[26:27], v[26:27], v[74:75], v[54:55]
	v_pk_fma_f32 v[20:21], v[20:21], v[72:73], v[60:61]
	v_pk_fma_f32 v[18:19], v[18:19], v[70:71], v[58:59]
	global_store_dwordx4 v[98:99], v[30:33], off
	global_store_dwordx4 v[98:99], v[26:29], off offset:64
	global_store_dwordx4 v[98:99], v[18:21], off offset:512
	s_waitcnt vmcnt(7)
	v_pk_fma_f32 v[12:13], v[24:25], v[80:81], v[48:49]
	v_pk_fma_f32 v[10:11], v[22:23], v[78:79], v[46:47]
	global_store_dwordx4 v[82:83], v[10:13], off
	s_waitcnt vmcnt(6)
	v_pk_fma_f32 v[8:9], v[8:9], v[72:73], v[40:41]
	v_pk_fma_f32 v[6:7], v[6:7], v[70:71], v[38:39]
	v_pk_fma_f32 v[12:13], v[16:17], v[76:77], v[44:45]
	v_pk_fma_f32 v[10:11], v[14:15], v[74:75], v[42:43]
	s_waitcnt vmcnt(5)
	v_pk_fma_f32 v[4:5], v[4:5], v[68:69], v[36:37]
	v_pk_fma_f32 v[2:3], v[2:3], v[66:67], v[34:35]
	global_store_dwordx4 v[82:83], v[10:13], off offset:64
	global_store_dwordx4 v[82:83], v[6:9], off offset:512
	global_store_dwordx4 v[82:83], v[2:5], off offset:576
	s_cbranch_vccz .LBB0_888
	s_waitcnt vmcnt(0)
	s_cmpk_gt_u32 s2, 0xff
	s_cbranch_scc1 .LBB0_899
	s_barrier
